# grid barrier: all WGs poll the cross-XCD arrival counter TOP for >= (round+1)*nx, last leader's TOPGEN post dropped
# speedup vs baseline: 1.0042x; 1.0042x over previous
.LBB0_73:
	s_or_b64 exec, exec, s[12:13]
	v_cvt_f32_u32_e32 v4, v2
	s_waitcnt vmcnt(0)
	v_readfirstlane_b32 s3, v3
	v_sub_u32_e32 v3, 0, v2
	v_rcp_iflag_f32_e32 v4, v4
	v_add_u32_e32 v5, s3, v1
	v_mul_f32_e32 v4, 0x4f7ffffe, v4
	v_cvt_u32_f32_e32 v4, v4
	v_mul_lo_u32 v1, v3, v4
	v_mul_hi_u32 v1, v4, v1
	v_add_u32_e32 v1, v4, v1
	v_mul_hi_u32 v1, v5, v1
	v_mul_lo_u32 v3, v1, v2
	v_sub_u32_e32 v3, v5, v3
	v_add_u32_e32 v4, 1, v1
	v_cmp_ge_u32_e32 vcc, v3, v2
	s_nop 1
	v_cndmask_b32_e32 v1, v1, v4, vcc
	v_sub_u32_e32 v4, v3, v2
	v_cndmask_b32_e32 v3, v3, v4, vcc
	v_add_u32_e32 v4, 1, v1
	v_cmp_ge_u32_e32 vcc, v3, v2
	v_add_u32_e32 v3, 1, v5
	s_nop 0
	v_cndmask_b32_e32 v1, v1, v4, vcc
	v_mul_lo_u32 v4, v2, v1
	v_add_u32_e32 v2, v4, v2
	v_cmp_ne_u32_e32 vcc, v3, v2
	s_and_saveexec_b64 s[10:11], vcc
	s_xor_b64 s[10:11], exec, s[10:11]
	s_cbranch_execz .LBB0_87
	s_waitcnt lgkmcnt(0)
	v_mad_u32_u24 v1, v1, v0, v0
	v_mov_b32_e32 v0, 0x7400
	global_load_dword v0, v0, s[96:97] sc1
	s_add_u32 s16, s96, 0x7400
	s_addc_u32 s17, s97, 0
	s_waitcnt vmcnt(0)
	v_cmp_lt_u32_e32 vcc, v0, v1
	s_and_saveexec_b64 s[12:13], vcc
	s_cbranch_execz .LBB0_86
	s_add_u32 s14, s96, 0x4200
	s_addc_u32 s15, s97, 0
	s_mov_b32 s3, 1
	s_mov_b64 s[18:19], 0
	v_mov_b32_e32 v0, 0
	s_branch .LBB0_77

.LBB0_79:
	global_load_dword v2, v0, s[16:17] sc1
	s_add_i32 s3, s3, 1
	s_mov_b64 s[24:25], -1
	s_waitcnt vmcnt(0)
	v_cmp_ge_u32_e32 vcc, v2, v1
	s_orn2_b64 s[22:23], vcc, exec
	s_branch .LBB0_76

.LBB0_90:
	s_or_b64 exec, exec, s[14:15]
	v_cvt_f32_u32_e32 v3, v0
	s_waitcnt vmcnt(0)
	v_readfirstlane_b32 s3, v2
	s_add_u32 s14, s96, 0x7400
	s_addc_u32 s15, s97, 0
	v_rcp_iflag_f32_e32 v3, v3
	v_add_u32_e32 v1, s3, v1
	v_add_u32_e32 v4, 1, v1
	s_mov_b64 s[16:17], 0
	v_mul_f32_e32 v2, 0x4f7ffffe, v3
	v_cvt_u32_f32_e32 v2, v2
	v_sub_u32_e32 v3, 0, v0
	v_mul_lo_u32 v3, v3, v2
	v_mul_hi_u32 v3, v2, v3
	v_add_u32_e32 v2, v2, v3
	v_mul_hi_u32 v2, v1, v2
	v_mul_lo_u32 v3, v2, v0
	v_sub_u32_e32 v1, v1, v3
	v_add_u32_e32 v5, 1, v2
	v_cmp_ge_u32_e32 vcc, v1, v0
	v_sub_u32_e32 v3, v1, v0
	s_nop 0
	v_cndmask_b32_e32 v2, v2, v5, vcc
	v_cndmask_b32_e32 v1, v1, v3, vcc
	v_add_u32_e32 v3, 1, v2
	v_cmp_ge_u32_e32 vcc, v1, v0
	s_nop 1
	v_cndmask_b32_e32 v2, v2, v3, vcc
	v_mul_lo_u32 v1, v0, v2
	v_add_u32_e32 v0, v1, v0
	v_mov_b32_e32 v2, v0
	v_cmp_ne_u32_e32 vcc, v4, v0
	v_mov_b64_e32 v[0:1], s[14:15]
	s_and_saveexec_b64 s[12:13], vcc
	s_cbranch_execz .LBB0_102
	v_mov_b32_e32 v0, 0
	global_load_dword v1, v0, s[14:15] sc1
	s_mov_b64 s[20:21], 0
	s_waitcnt vmcnt(0)
	v_cmp_lt_u32_e32 vcc, v1, v2
	s_and_saveexec_b64 s[18:19], vcc
	s_cbranch_execz .LBB0_101
	s_add_u32 s16, s96, 0x4200
	s_addc_u32 s17, s97, 0
	s_mov_b32 s3, 1
	s_branch .LBB0_94

.LBB0_96:
	global_load_dword v1, v0, s[14:15] sc1
	s_add_i32 s3, s3, 1
	s_mov_b64 s[24:25], -1
	s_waitcnt vmcnt(0)
	v_cmp_ge_u32_e32 vcc, v1, v2
	s_orn2_b64 s[28:29], vcc, exec
	s_branch .LBB0_93

.LBB0_146:
	s_or_b64 exec, exec, s[12:13]
	v_cvt_f32_u32_e32 v3, v0
	s_waitcnt vmcnt(0)
	v_readfirstlane_b32 s3, v2
	s_add_u32 s12, s96, 0x7400
	s_addc_u32 s13, s97, 0
	v_rcp_iflag_f32_e32 v3, v3
	v_add_u32_e32 v1, s3, v1
	v_add_u32_e32 v4, 1, v1
	s_mov_b64 s[14:15], 0
	v_mul_f32_e32 v2, 0x4f7ffffe, v3
	v_cvt_u32_f32_e32 v2, v2
	v_sub_u32_e32 v3, 0, v0
	v_mul_lo_u32 v3, v3, v2
	v_mul_hi_u32 v3, v2, v3
	v_add_u32_e32 v2, v2, v3
	v_mul_hi_u32 v2, v1, v2
	v_mul_lo_u32 v3, v2, v0
	v_sub_u32_e32 v1, v1, v3
	v_add_u32_e32 v5, 1, v2
	v_cmp_ge_u32_e32 vcc, v1, v0
	v_sub_u32_e32 v3, v1, v0
	s_nop 0
	v_cndmask_b32_e32 v2, v2, v5, vcc
	v_cndmask_b32_e32 v1, v1, v3, vcc
	v_add_u32_e32 v3, 1, v2
	v_cmp_ge_u32_e32 vcc, v1, v0
	s_nop 1
	v_cndmask_b32_e32 v2, v2, v3, vcc
	v_mul_lo_u32 v1, v0, v2
	v_add_u32_e32 v0, v1, v0
	v_mov_b32_e32 v2, v0
	v_cmp_ne_u32_e32 vcc, v4, v0
	v_mov_b64_e32 v[0:1], s[12:13]
	s_and_saveexec_b64 s[10:11], vcc
	s_cbranch_execz .LBB0_158
	v_mov_b32_e32 v0, 0
	global_load_dword v1, v0, s[12:13] sc1
	s_mov_b64 s[18:19], 0
	s_waitcnt vmcnt(0)
	v_cmp_lt_u32_e32 vcc, v1, v2
	s_and_saveexec_b64 s[16:17], vcc
	s_cbranch_execz .LBB0_157
	s_add_u32 s14, s96, 0x4200
	s_addc_u32 s15, s97, 0
	s_mov_b32 s3, 1
	s_branch .LBB0_150

.LBB0_152:
	global_load_dword v1, v0, s[12:13] sc1
	s_add_i32 s3, s3, 1
	s_mov_b64 s[22:23], -1
	s_waitcnt vmcnt(0)
	v_cmp_ge_u32_e32 vcc, v1, v2
	s_orn2_b64 s[26:27], vcc, exec
	s_branch .LBB0_149

.LBB0_401:
	s_or_b64 exec, exec, s[12:13]
	v_cvt_f32_u32_e32 v4, v2
	s_waitcnt vmcnt(0)
	v_readfirstlane_b32 s3, v3
	v_sub_u32_e32 v3, 0, v2
	v_rcp_iflag_f32_e32 v4, v4
	v_add_u32_e32 v5, s3, v1
	v_mul_f32_e32 v4, 0x4f7ffffe, v4
	v_cvt_u32_f32_e32 v4, v4
	v_mul_lo_u32 v1, v3, v4
	v_mul_hi_u32 v1, v4, v1
	v_add_u32_e32 v1, v4, v1
	v_mul_hi_u32 v1, v5, v1
	v_mul_lo_u32 v3, v1, v2
	v_sub_u32_e32 v3, v5, v3
	v_add_u32_e32 v4, 1, v1
	v_cmp_ge_u32_e32 vcc, v3, v2
	s_nop 1
	v_cndmask_b32_e32 v1, v1, v4, vcc
	v_sub_u32_e32 v4, v3, v2
	v_cndmask_b32_e32 v3, v3, v4, vcc
	v_add_u32_e32 v4, 1, v1
	v_cmp_ge_u32_e32 vcc, v3, v2
	v_add_u32_e32 v3, 1, v5
	s_nop 0
	v_cndmask_b32_e32 v1, v1, v4, vcc
	v_mul_lo_u32 v4, v2, v1
	v_add_u32_e32 v2, v4, v2
	v_cmp_ne_u32_e32 vcc, v3, v2
	s_and_saveexec_b64 s[10:11], vcc
	s_xor_b64 s[10:11], exec, s[10:11]
	s_cbranch_execz .LBB0_415
	s_waitcnt lgkmcnt(0)
	v_mad_u32_u24 v1, v1, v0, v0
	v_mov_b32_e32 v0, 0x7400
	global_load_dword v0, v0, s[96:97] sc1
	s_add_u32 s16, s96, 0x7400
	s_addc_u32 s17, s97, 0
	s_waitcnt vmcnt(0)
	v_cmp_lt_u32_e32 vcc, v0, v1
	s_and_saveexec_b64 s[12:13], vcc
	s_cbranch_execz .LBB0_414
	s_add_u32 s14, s96, 0x4200
	s_addc_u32 s15, s97, 0
	s_mov_b32 s3, 1
	s_mov_b64 s[20:21], 0
	v_mov_b32_e32 v0, 0
	s_branch .LBB0_405

.LBB0_407:
	global_load_dword v2, v0, s[16:17] sc1
	s_add_i32 s3, s3, 1
	s_mov_b64 s[26:27], -1
	s_waitcnt vmcnt(0)
	v_cmp_ge_u32_e32 vcc, v2, v1
	s_orn2_b64 s[24:25], vcc, exec
	s_branch .LBB0_404

.LBB0_418:
	s_or_b64 exec, exec, s[12:13]
	v_cvt_f32_u32_e32 v3, v0
	s_waitcnt vmcnt(0)
	v_readfirstlane_b32 s3, v2
	s_add_u32 s12, s96, 0x7400
	s_addc_u32 s13, s97, 0
	v_rcp_iflag_f32_e32 v3, v3
	v_add_u32_e32 v1, s3, v1
	v_add_u32_e32 v4, 1, v1
	s_mov_b64 s[14:15], 0
	v_mul_f32_e32 v2, 0x4f7ffffe, v3
	v_cvt_u32_f32_e32 v2, v2
	v_sub_u32_e32 v3, 0, v0
	v_mul_lo_u32 v3, v3, v2
	v_mul_hi_u32 v3, v2, v3
	v_add_u32_e32 v2, v2, v3
	v_mul_hi_u32 v2, v1, v2
	v_mul_lo_u32 v3, v2, v0
	v_sub_u32_e32 v1, v1, v3
	v_add_u32_e32 v5, 1, v2
	v_cmp_ge_u32_e32 vcc, v1, v0
	v_sub_u32_e32 v3, v1, v0
	s_nop 0
	v_cndmask_b32_e32 v2, v2, v5, vcc
	v_cndmask_b32_e32 v1, v1, v3, vcc
	v_add_u32_e32 v3, 1, v2
	v_cmp_ge_u32_e32 vcc, v1, v0
	s_nop 1
	v_cndmask_b32_e32 v2, v2, v3, vcc
	v_mul_lo_u32 v1, v0, v2
	v_add_u32_e32 v0, v1, v0
	v_mov_b32_e32 v2, v0
	v_cmp_ne_u32_e32 vcc, v4, v0
	v_mov_b64_e32 v[0:1], s[12:13]
	s_and_saveexec_b64 s[10:11], vcc
	s_cbranch_execz .LBB0_430
	v_mov_b32_e32 v0, 0
	global_load_dword v1, v0, s[12:13] sc1
	s_mov_b64 s[20:21], 0
	s_waitcnt vmcnt(0)
	v_cmp_lt_u32_e32 vcc, v1, v2
	s_and_saveexec_b64 s[16:17], vcc
	s_cbranch_execz .LBB0_429
	s_add_u32 s14, s96, 0x4200
	s_addc_u32 s15, s97, 0
	s_mov_b32 s3, 1
	s_branch .LBB0_422

.LBB0_424:
	global_load_dword v1, v0, s[12:13] sc1
	s_add_i32 s3, s3, 1
	s_mov_b64 s[24:25], -1
	s_waitcnt vmcnt(0)
	v_cmp_ge_u32_e32 vcc, v1, v2
	s_orn2_b64 s[28:29], vcc, exec
	s_branch .LBB0_421

.LBB0_459:
	s_or_b64 exec, exec, s[10:11]
	v_cvt_f32_u32_e32 v4, v2
	s_waitcnt vmcnt(0)
	v_readfirstlane_b32 s3, v3
	v_sub_u32_e32 v3, 0, v2
	v_rcp_iflag_f32_e32 v4, v4
	v_add_u32_e32 v5, s3, v1
	v_mul_f32_e32 v4, 0x4f7ffffe, v4
	v_cvt_u32_f32_e32 v4, v4
	v_mul_lo_u32 v1, v3, v4
	v_mul_hi_u32 v1, v4, v1
	v_add_u32_e32 v1, v4, v1
	v_mul_hi_u32 v1, v5, v1
	v_mul_lo_u32 v3, v1, v2
	v_sub_u32_e32 v3, v5, v3
	v_add_u32_e32 v4, 1, v1
	v_cmp_ge_u32_e32 vcc, v3, v2
	s_nop 1
	v_cndmask_b32_e32 v1, v1, v4, vcc
	v_sub_u32_e32 v4, v3, v2
	v_cndmask_b32_e32 v3, v3, v4, vcc
	v_add_u32_e32 v4, 1, v1
	v_cmp_ge_u32_e32 vcc, v3, v2
	v_add_u32_e32 v3, 1, v5
	s_nop 0
	v_cndmask_b32_e32 v1, v1, v4, vcc
	v_mul_lo_u32 v4, v2, v1
	v_add_u32_e32 v2, v4, v2
	v_cmp_ne_u32_e32 vcc, v3, v2
	s_and_saveexec_b64 s[8:9], vcc
	s_xor_b64 s[8:9], exec, s[8:9]
	s_cbranch_execz .LBB0_473
	s_waitcnt lgkmcnt(0)
	v_mad_u32_u24 v1, v1, v0, v0
	v_mov_b32_e32 v0, 0x7400
	global_load_dword v0, v0, s[96:97] sc1
	s_add_u32 s14, s96, 0x7400
	s_addc_u32 s15, s97, 0
	s_waitcnt vmcnt(0)
	v_cmp_lt_u32_e32 vcc, v0, v1
	s_and_saveexec_b64 s[10:11], vcc
	s_cbranch_execz .LBB0_472
	s_add_u32 s12, s96, 0x4200
	s_addc_u32 s13, s97, 0
	s_mov_b32 s3, 1
	s_mov_b64 s[16:17], 0
	v_mov_b32_e32 v0, 0
	s_branch .LBB0_463

.LBB0_465:
	global_load_dword v2, v0, s[14:15] sc1
	s_add_i32 s3, s3, 1
	s_mov_b64 s[24:25], -1
	s_waitcnt vmcnt(0)
	v_cmp_ge_u32_e32 vcc, v2, v1
	s_orn2_b64 s[22:23], vcc, exec
	s_branch .LBB0_462

.LBB0_476:
	s_or_b64 exec, exec, s[10:11]
	v_cvt_f32_u32_e32 v3, v0
	s_waitcnt vmcnt(0)
	v_readfirstlane_b32 s3, v2
	s_add_u32 s10, s96, 0x7400
	s_addc_u32 s11, s97, 0
	v_rcp_iflag_f32_e32 v3, v3
	v_add_u32_e32 v1, s3, v1
	v_add_u32_e32 v4, 1, v1
	s_mov_b64 s[12:13], 0
	v_mul_f32_e32 v2, 0x4f7ffffe, v3
	v_cvt_u32_f32_e32 v2, v2
	v_sub_u32_e32 v3, 0, v0
	v_mul_lo_u32 v3, v3, v2
	v_mul_hi_u32 v3, v2, v3
	v_add_u32_e32 v2, v2, v3
	v_mul_hi_u32 v2, v1, v2
	v_mul_lo_u32 v3, v2, v0
	v_sub_u32_e32 v1, v1, v3
	v_add_u32_e32 v5, 1, v2
	v_cmp_ge_u32_e32 vcc, v1, v0
	v_sub_u32_e32 v3, v1, v0
	s_nop 0
	v_cndmask_b32_e32 v2, v2, v5, vcc
	v_cndmask_b32_e32 v1, v1, v3, vcc
	v_add_u32_e32 v3, 1, v2
	v_cmp_ge_u32_e32 vcc, v1, v0
	s_nop 1
	v_cndmask_b32_e32 v2, v2, v3, vcc
	v_mul_lo_u32 v1, v0, v2
	v_add_u32_e32 v0, v1, v0
	v_mov_b32_e32 v2, v0
	v_cmp_ne_u32_e32 vcc, v4, v0
	v_mov_b64_e32 v[0:1], s[10:11]
	s_and_saveexec_b64 s[8:9], vcc
	s_cbranch_execz .LBB0_488
	v_mov_b32_e32 v0, 0
	global_load_dword v1, v0, s[10:11] sc1
	s_mov_b64 s[16:17], 0
	s_waitcnt vmcnt(0)
	v_cmp_lt_u32_e32 vcc, v1, v2
	s_and_saveexec_b64 s[14:15], vcc
	s_cbranch_execz .LBB0_487
	s_add_u32 s12, s96, 0x4200
	s_addc_u32 s13, s97, 0
	s_mov_b32 s3, 1
	s_branch .LBB0_480

.LBB0_482:
	global_load_dword v1, v0, s[10:11] sc1
	s_add_i32 s3, s3, 1
	s_mov_b64 s[22:23], -1
	s_waitcnt vmcnt(0)
	v_cmp_ge_u32_e32 vcc, v1, v2
	s_orn2_b64 s[26:27], vcc, exec
	s_branch .LBB0_479

.LBB0_662:
	global_load_dword v2, v0, s[14:15] sc1
	s_add_i32 s3, s3, 1
	s_mov_b64 s[26:27], -1
	s_waitcnt vmcnt(0)
	v_cmp_ge_u32_e32 vcc, v2, v1
	s_orn2_b64 s[24:25], vcc, exec
	s_branch .LBB0_659

.LBB0_679:
	global_load_dword v1, v0, s[10:11] sc1
	s_add_i32 s3, s3, 1
	s_mov_b64 s[24:25], -1
	s_waitcnt vmcnt(0)
	v_cmp_ge_u32_e32 vcc, v1, v2
	s_orn2_b64 s[28:29], vcc, exec
	s_branch .LBB0_676

.LBB0_1168:
	s_or_b64 exec, exec, s[14:15]
	v_cvt_f32_u32_e32 v4, v2
	s_waitcnt vmcnt(0)
	v_readfirstlane_b32 s3, v3
	v_sub_u32_e32 v3, 0, v2
	v_rcp_iflag_f32_e32 v4, v4
	v_add_u32_e32 v5, s3, v1
	v_mul_f32_e32 v4, 0x4f7ffffe, v4
	v_cvt_u32_f32_e32 v4, v4
	v_mul_lo_u32 v1, v3, v4
	v_mul_hi_u32 v1, v4, v1
	v_add_u32_e32 v1, v4, v1
	v_mul_hi_u32 v1, v5, v1
	v_mul_lo_u32 v3, v1, v2
	v_sub_u32_e32 v3, v5, v3
	v_add_u32_e32 v4, 1, v1
	v_cmp_ge_u32_e32 vcc, v3, v2
	s_nop 1
	v_cndmask_b32_e32 v1, v1, v4, vcc
	v_sub_u32_e32 v4, v3, v2
	v_cndmask_b32_e32 v3, v3, v4, vcc
	v_add_u32_e32 v4, 1, v1
	v_cmp_ge_u32_e32 vcc, v3, v2
	v_add_u32_e32 v3, 1, v5
	s_nop 0
	v_cndmask_b32_e32 v1, v1, v4, vcc
	v_mul_lo_u32 v4, v2, v1
	v_add_u32_e32 v2, v4, v2
	v_cmp_ne_u32_e32 vcc, v3, v2
	s_and_saveexec_b64 s[10:11], vcc
	s_xor_b64 s[10:11], exec, s[10:11]
	s_cbranch_execz .LBB0_1182
	s_waitcnt lgkmcnt(0)
	v_mad_u32_u24 v1, v1, v0, v0
	v_mov_b32_e32 v0, 0x7400
	global_load_dword v0, v0, s[96:97] sc1
	s_add_u32 s20, s96, 0x7400
	s_addc_u32 s21, s97, 0
	s_waitcnt vmcnt(0)
	v_cmp_lt_u32_e32 vcc, v0, v1
	s_and_saveexec_b64 s[14:15], vcc
	s_cbranch_execz .LBB0_1181
	s_add_u32 s16, s96, 0x4200
	s_addc_u32 s17, s97, 0
	s_mov_b32 s3, 1
	s_mov_b64 s[22:23], 0
	v_mov_b32_e32 v0, 0
	s_branch .LBB0_1172

.LBB0_1174:
	global_load_dword v2, v0, s[20:21] sc1
	s_add_i32 s3, s3, 1
	s_mov_b64 s[28:29], -1
	s_waitcnt vmcnt(0)
	v_cmp_ge_u32_e32 vcc, v2, v1
	s_orn2_b64 s[26:27], vcc, exec
	s_branch .LBB0_1171

.LBB0_1185:
	s_or_b64 exec, exec, s[14:15]
	v_cvt_f32_u32_e32 v3, v0
	s_waitcnt vmcnt(0)
	v_readfirstlane_b32 s3, v2
	s_add_u32 s14, s96, 0x7400
	s_addc_u32 s15, s97, 0
	v_rcp_iflag_f32_e32 v3, v3
	v_add_u32_e32 v1, s3, v1
	v_add_u32_e32 v4, 1, v1
	s_mov_b64 s[16:17], 0
	v_mul_f32_e32 v2, 0x4f7ffffe, v3
	v_cvt_u32_f32_e32 v2, v2
	v_sub_u32_e32 v3, 0, v0
	v_mul_lo_u32 v3, v3, v2
	v_mul_hi_u32 v3, v2, v3
	v_add_u32_e32 v2, v2, v3
	v_mul_hi_u32 v2, v1, v2
	v_mul_lo_u32 v3, v2, v0
	v_sub_u32_e32 v1, v1, v3
	v_add_u32_e32 v5, 1, v2
	v_cmp_ge_u32_e32 vcc, v1, v0
	v_sub_u32_e32 v3, v1, v0
	s_nop 0
	v_cndmask_b32_e32 v2, v2, v5, vcc
	v_cndmask_b32_e32 v1, v1, v3, vcc
	v_add_u32_e32 v3, 1, v2
	v_cmp_ge_u32_e32 vcc, v1, v0
	s_nop 1
	v_cndmask_b32_e32 v2, v2, v3, vcc
	v_mul_lo_u32 v1, v0, v2
	v_add_u32_e32 v0, v1, v0
	v_mov_b32_e32 v2, v0
	v_cmp_ne_u32_e32 vcc, v4, v0
	v_mov_b64_e32 v[0:1], s[14:15]
	s_and_saveexec_b64 s[10:11], vcc
	s_cbranch_execz .LBB0_1197
	v_mov_b32_e32 v0, 0
	global_load_dword v1, v0, s[14:15] sc1
	s_mov_b64 s[22:23], 0
	s_waitcnt vmcnt(0)
	v_cmp_lt_u32_e32 vcc, v1, v2
	s_and_saveexec_b64 s[20:21], vcc
	s_cbranch_execz .LBB0_1196
	s_add_u32 s16, s96, 0x4200
	s_addc_u32 s17, s97, 0
	s_mov_b32 s3, 1
	s_branch .LBB0_1189

.LBB0_1191:
	global_load_dword v1, v0, s[14:15] sc1
	s_add_i32 s3, s3, 1
	s_mov_b64 s[26:27], -1
	s_waitcnt vmcnt(0)
	v_cmp_ge_u32_e32 vcc, v1, v2
	s_orn2_b64 s[30:31], vcc, exec
	s_branch .LBB0_1188

.LBB0_1268:
	s_or_b64 exec, exec, s[14:15]
	v_cvt_f32_u32_e32 v4, v2
	s_waitcnt vmcnt(0)
	v_readfirstlane_b32 s3, v3
	v_sub_u32_e32 v3, 0, v2
	v_rcp_iflag_f32_e32 v4, v4
	v_add_u32_e32 v5, s3, v1
	v_mul_f32_e32 v4, 0x4f7ffffe, v4
	v_cvt_u32_f32_e32 v4, v4
	v_mul_lo_u32 v1, v3, v4
	v_mul_hi_u32 v1, v4, v1
	v_add_u32_e32 v1, v4, v1
	v_mul_hi_u32 v1, v5, v1
	v_mul_lo_u32 v3, v1, v2
	v_sub_u32_e32 v3, v5, v3
	v_add_u32_e32 v4, 1, v1
	v_cmp_ge_u32_e32 vcc, v3, v2
	s_nop 1
	v_cndmask_b32_e32 v1, v1, v4, vcc
	v_sub_u32_e32 v4, v3, v2
	v_cndmask_b32_e32 v3, v3, v4, vcc
	v_add_u32_e32 v4, 1, v1
	v_cmp_ge_u32_e32 vcc, v3, v2
	v_add_u32_e32 v3, 1, v5
	s_nop 0
	v_cndmask_b32_e32 v1, v1, v4, vcc
	v_mul_lo_u32 v4, v2, v1
	v_add_u32_e32 v2, v4, v2
	v_cmp_ne_u32_e32 vcc, v3, v2
	s_and_saveexec_b64 s[10:11], vcc
	s_xor_b64 s[10:11], exec, s[10:11]
	s_cbranch_execz .LBB0_1282
	s_waitcnt lgkmcnt(0)
	v_mad_u32_u24 v1, v1, v0, v0
	v_mov_b32_e32 v0, 0x7400
	global_load_dword v0, v0, s[96:97] sc1
	s_add_u32 s18, s96, 0x7400
	s_addc_u32 s19, s97, 0
	s_waitcnt vmcnt(0)
	v_cmp_lt_u32_e32 vcc, v0, v1
	s_and_saveexec_b64 s[14:15], vcc
	s_cbranch_execz .LBB0_1281
	s_add_u32 s16, s96, 0x4200
	s_addc_u32 s17, s97, 0
	s_mov_b32 s3, 1
	s_mov_b64 s[20:21], 0
	v_mov_b32_e32 v0, 0
	s_branch .LBB0_1272

.LBB0_1274:
	global_load_dword v2, v0, s[18:19] sc1
	s_add_i32 s3, s3, 1
	s_mov_b64 s[26:27], -1
	s_waitcnt vmcnt(0)
	v_cmp_ge_u32_e32 vcc, v2, v1
	s_orn2_b64 s[24:25], vcc, exec
	s_branch .LBB0_1271

.LBB0_1285:
	s_or_b64 exec, exec, s[14:15]
	v_cvt_f32_u32_e32 v3, v0
	s_waitcnt vmcnt(0)
	v_readfirstlane_b32 s3, v2
	s_add_u32 s14, s96, 0x7400
	s_addc_u32 s15, s97, 0
	v_rcp_iflag_f32_e32 v3, v3
	v_add_u32_e32 v1, s3, v1
	v_add_u32_e32 v4, 1, v1
	s_mov_b64 s[16:17], 0
	v_mul_f32_e32 v2, 0x4f7ffffe, v3
	v_cvt_u32_f32_e32 v2, v2
	v_sub_u32_e32 v3, 0, v0
	v_mul_lo_u32 v3, v3, v2
	v_mul_hi_u32 v3, v2, v3
	v_add_u32_e32 v2, v2, v3
	v_mul_hi_u32 v2, v1, v2
	v_mul_lo_u32 v3, v2, v0
	v_sub_u32_e32 v1, v1, v3
	v_add_u32_e32 v5, 1, v2
	v_cmp_ge_u32_e32 vcc, v1, v0
	v_sub_u32_e32 v3, v1, v0
	s_nop 0
	v_cndmask_b32_e32 v2, v2, v5, vcc
	v_cndmask_b32_e32 v1, v1, v3, vcc
	v_add_u32_e32 v3, 1, v2
	v_cmp_ge_u32_e32 vcc, v1, v0
	s_nop 1
	v_cndmask_b32_e32 v2, v2, v3, vcc
	v_mul_lo_u32 v1, v0, v2
	v_add_u32_e32 v0, v1, v0
	v_mov_b32_e32 v2, v0
	v_cmp_ne_u32_e32 vcc, v4, v0
	v_mov_b64_e32 v[0:1], s[14:15]
	s_and_saveexec_b64 s[10:11], vcc
	s_cbranch_execz .LBB0_1297
	v_mov_b32_e32 v0, 0
	global_load_dword v1, v0, s[14:15] sc1
	s_mov_b64 s[20:21], 0
	s_waitcnt vmcnt(0)
	v_cmp_lt_u32_e32 vcc, v1, v2
	s_and_saveexec_b64 s[18:19], vcc
	s_cbranch_execz .LBB0_1296
	s_add_u32 s16, s96, 0x4200
	s_addc_u32 s17, s97, 0
	s_mov_b32 s3, 1
	s_branch .LBB0_1289

.LBB0_1393:
	s_or_b64 exec, exec, s[14:15]
	v_cvt_f32_u32_e32 v4, v2
	s_waitcnt vmcnt(0)
	v_readfirstlane_b32 s3, v3
	v_sub_u32_e32 v3, 0, v2
	v_rcp_iflag_f32_e32 v4, v4
	v_add_u32_e32 v5, s3, v1
	v_mul_f32_e32 v4, 0x4f7ffffe, v4
	v_cvt_u32_f32_e32 v4, v4
	v_mul_lo_u32 v1, v3, v4
	v_mul_hi_u32 v1, v4, v1
	v_add_u32_e32 v1, v4, v1
	v_mul_hi_u32 v1, v5, v1
	v_mul_lo_u32 v3, v1, v2
	v_sub_u32_e32 v3, v5, v3
	v_add_u32_e32 v4, 1, v1
	v_cmp_ge_u32_e32 vcc, v3, v2
	s_nop 1
	v_cndmask_b32_e32 v1, v1, v4, vcc
	v_sub_u32_e32 v4, v3, v2
	v_cndmask_b32_e32 v3, v3, v4, vcc
	v_add_u32_e32 v4, 1, v1
	v_cmp_ge_u32_e32 vcc, v3, v2
	v_add_u32_e32 v3, 1, v5
	s_nop 0
	v_cndmask_b32_e32 v1, v1, v4, vcc
	v_mul_lo_u32 v4, v2, v1
	v_add_u32_e32 v2, v4, v2
	v_cmp_ne_u32_e32 vcc, v3, v2
	s_and_saveexec_b64 s[12:13], vcc
	s_xor_b64 s[12:13], exec, s[12:13]
	s_cbranch_execz .LBB0_1407
	s_waitcnt lgkmcnt(0)
	v_mad_u32_u24 v1, v1, v0, v0
	v_mov_b32_e32 v0, 0x7400
	global_load_dword v0, v0, s[96:97] sc1
	s_add_u32 s18, s96, 0x7400
	s_addc_u32 s19, s97, 0
	s_waitcnt vmcnt(0)
	v_cmp_lt_u32_e32 vcc, v0, v1
	s_and_saveexec_b64 s[14:15], vcc
	s_cbranch_execz .LBB0_1406
	s_add_u32 s16, s96, 0x4200
	s_addc_u32 s17, s97, 0
	s_mov_b32 s3, 1
	s_mov_b64 s[20:21], 0
	v_mov_b32_e32 v0, 0
	s_branch .LBB0_1397
